# v45 with the INB parked stores issued in K-loop iterations 2-7
# speedup vs baseline: 1.0103x; 1.0015x over previous
; #define PG8_STAGE(bufoff, gbase, voff) do { _Pragma("unroll") for (int _i = 0; _i < 2; ++_i) \
;         __builtin_amdgcn_global_load_lds((const unsigned*)((const char*)(gbase) + (voff)[_i]), (PG8_LAS unsigned*)(lds + (bufoff) + ldsw + _i * 8192), 16, 0, 0); } while (0)
; #define PG8_LDA(dst, b, h) do { _Pragma("unroll") for (int m = 0; m < 4; ++m) _Pragma("unroll") for (int k = 0; k < 2; ++k) dst[m][k] = *(const PG8_LAS bf16x8*)(lds + PG8_SA(b, h) + aoff + m * 2048 + k * 1024); } while (0)
; #define PG8_LDB(dst, b, h) do { _Pragma("unroll") for (int n = 0; n < 2; ++n) _Pragma("unroll") for (int k = 0; k < 2; ++k) dst[n][k] = *(const PG8_LAS bf16x8*)(lds + PG8_SB(b, h) + boff + n * 2048 + k * 1024); } while (0)
; #define PG8_SCHED __builtin_amdgcn_sched_barrier(0)
;     ...
;             const char* a2 = last ? nA : cA + (size_t)(t + 2) * kstep; const char* b2 = last ? nB : cB + (size_t)(t + 2) * kstep;
;             const char* a3 = a2 + kstep; const char* b3 = b2 + kstep;
;             PG8_LDB(B0, 0, 0); PG8_LDB(B1, 0, 1); PG8_SCHED; PG8_LDA(At, 0, 0); PG8_STAGE(PG8_SA(1, 1), a1 + hstep, voffA);
.LBB0_532:
	s_waitcnt lgkmcnt(0)
	v_add_u32_e32 v124, s51, v197
	s_waitcnt lgkmcnt(0)
	v_add_u32_e32 v156, s52, v197
	ds_read_b128 v[112:115], v124
	ds_read_b128 v[116:119], v124 offset:1024
	ds_read_b128 v[120:123], v124 offset:2048
	ds_read_b128 v[124:127], v124 offset:3072
	ds_read_b128 v[144:147], v156
	ds_read_b128 v[148:151], v156 offset:1024
	ds_read_b128 v[152:155], v156 offset:2048
	ds_read_b128 v[156:159], v156 offset:3072
	s_add_u32 s22, s24, 0xfffc0080
	s_addc_u32 s23, s25, -1
	s_cmp_eq_u32 s56, 12
	s_cselect_b32 s27, s2, s23
	s_cselect_b32 s26, s5, s22
	s_cselect_b32 s23, s7, s55
	s_cselect_b32 s22, s17, s39
	v_lshl_add_u64 v[218:219], s[24:25], 0, v[184:185]
	s_add_i32 m0, s29, 0xc000
	ds_read_b128 v[160:163], v200
	ds_read_b128 v[164:167], v200 offset:1024
	ds_read_b128 v[168:171], v200 offset:2048
	ds_read_b128 v[192:195], v200 offset:3072
	ds_read_b128 v[202:205], v200 offset:4096
	ds_read_b128 v[206:209], v200 offset:5120
	ds_read_b128 v[210:213], v200 offset:6144
	ds_read_b128 v[214:217], v200 offset:7168
	global_load_lds_dwordx4 v[218:219], off
	v_lshl_add_u64 v[218:219], s[24:25], 0, v[186:187]
	s_add_i32 m0, s29, 0xe000
	s_nop 0
	global_load_lds_dwordx4 v[218:219], off
	s_and_b32 s101, s101, 0xff
	s_cbranch_scc0 .Lpkb_w8a
	s_cmp_lt_i32 s56, 2
	s_cbranch_scc1 .Lpkb_w8a
	s_cmp_eq_u32 s101, 6
	s_cbranch_scc1 .Lpkb_s0
	s_cmp_eq_u32 s101, 5
	s_cbranch_scc1 .Lpkb_s1
	s_cmp_eq_u32 s101, 4
	s_cbranch_scc1 .Lpkb_s2
	s_cmp_eq_u32 s101, 3
	s_cbranch_scc1 .Lpkb_s3
	s_cmp_eq_u32 s101, 2
	s_cbranch_scc1 .Lpkb_s4
	global_store_dwordx4 v[254:255], v[248:251], off offset:64
	s_branch .Lpkb_w9a

; #define PG8_STAGE(bufoff, gbase, voff) do { _Pragma("unroll") for (int _i = 0; _i < 2; ++_i) \
;         __builtin_amdgcn_global_load_lds((const unsigned*)((const char*)(gbase) + (voff)[_i]), (PG8_LAS unsigned*)(lds + (bufoff) + ldsw + _i * 8192), 16, 0, 0); } while (0)
; #define PG8_LDA(dst, b, h) do { _Pragma("unroll") for (int m = 0; m < 4; ++m) _Pragma("unroll") for (int k = 0; k < 2; ++k) dst[m][k] = *(const PG8_LAS bf16x8*)(lds + PG8_SA(b, h) + aoff + m * 2048 + k * 1024); } while (0)
; #define PG8_LDB(dst, b, h) do { _Pragma("unroll") for (int n = 0; n < 2; ++n) _Pragma("unroll") for (int k = 0; k < 2; ++k) dst[n][k] = *(const PG8_LAS bf16x8*)(lds + PG8_SB(b, h) + boff + n * 2048 + k * 1024); } while (0)
; #define PG8_WAIT_V(n) asm volatile("s_waitcnt vmcnt(" #n ")" ::: "memory")
; #define PG8_WAIT_L(n) asm volatile("s_waitcnt lgkmcnt(" #n ")" ::: "memory")
; #define PG8_BAR __builtin_amdgcn_s_barrier()
; #define PG8_SCHED __builtin_amdgcn_sched_barrier(0)
;     ...
;             PG8_LDB(B0, 0, 0); PG8_LDB(B1, 0, 1); PG8_SCHED; PG8_LDA(At, 0, 0); PG8_STAGE(PG8_SA(1, 1), a1 + hstep, voffA);
;             PG8_WAIT_V(8); PG8_WAIT_L(0); PG8_BAR; PG8_MMA(0, 0, At, B0); PG8_MMA(0, 1, At, B1); PG8_BAR; PG8_SCHED;
.Lpkb_w9a:
	s_bitset1_b32 s101, 16
	s_waitcnt vmcnt(9)
	s_branch .Lpkb_da

; #define PG8_STAGE(bufoff, gbase, voff) do { _Pragma("unroll") for (int _i = 0; _i < 2; ++_i) \
;         __builtin_amdgcn_global_load_lds((const unsigned*)((const char*)(gbase) + (voff)[_i]), (PG8_LAS unsigned*)(lds + (bufoff) + ldsw + _i * 8192), 16, 0, 0); } while (0)
; #define PG8_LDA(dst, b, h) do { _Pragma("unroll") for (int m = 0; m < 4; ++m) _Pragma("unroll") for (int k = 0; k < 2; ++k) dst[m][k] = *(const PG8_LAS bf16x8*)(lds + PG8_SA(b, h) + aoff + m * 2048 + k * 1024); } while (0)
; #define PG8_WAIT_V(n) asm volatile("s_waitcnt vmcnt(" #n ")" ::: "memory")
; #define PG8_WAIT_L(n) asm volatile("s_waitcnt lgkmcnt(" #n ")" ::: "memory")
; #define PG8_BAR __builtin_amdgcn_s_barrier()
; #define PG8_SCHED __builtin_amdgcn_sched_barrier(0)
;     ...
;             PG8_WAIT_V(8); PG8_WAIT_L(0); PG8_BAR; PG8_MMA(0, 0, At, B0); PG8_MMA(0, 1, At, B1); PG8_BAR; PG8_SCHED;
;             PG8_LDA(At, 0, 1); PG8_STAGE(PG8_SB(0, 0), b2, voffB); PG8_STAGE(PG8_SB(0, 1), b2 + hstepB, voffB); PG8_STAGE(PG8_SA(0, 0), a2, voffA);
.Lpkb_da:
	s_waitcnt lgkmcnt(0)
	s_barrier
	s_setprio 1
	s_waitcnt lgkmcnt(0)
	v_mfma_f32_16x16x32_f16 v[132:135], v[112:115], v[160:163], v[132:135]
	v_mfma_f32_16x16x32_f16 v[128:131], v[120:123], v[160:163], v[128:131]
	v_mfma_f32_16x16x32_f16 v[100:103], v[112:115], v[168:171], v[100:103]
	v_mfma_f32_16x16x32_f16 v[96:99], v[120:123], v[168:171], v[96:99]
	v_mfma_f32_16x16x32_f16 v[84:87], v[112:115], v[202:205], v[84:87]
	v_mfma_f32_16x16x32_f16 v[80:83], v[120:123], v[202:205], v[80:83]
	v_mfma_f32_16x16x32_f16 v[68:71], v[112:115], v[210:213], v[68:71]
	v_mfma_f32_16x16x32_f16 v[64:67], v[120:123], v[210:213], v[64:67]
	v_mfma_f32_16x16x32_f16 v[132:135], v[116:119], v[164:167], v[132:135]
	v_mfma_f32_16x16x32_f16 v[128:131], v[124:127], v[164:167], v[128:131]
	v_mfma_f32_16x16x32_f16 v[100:103], v[116:119], v[192:195], v[100:103]
	v_mfma_f32_16x16x32_f16 v[96:99], v[124:127], v[192:195], v[96:99]
	v_mfma_f32_16x16x32_f16 v[84:87], v[116:119], v[206:209], v[84:87]
	v_mfma_f32_16x16x32_f16 v[80:83], v[124:127], v[206:209], v[80:83]
	v_mfma_f32_16x16x32_f16 v[68:71], v[116:119], v[214:217], v[68:71]
	v_mfma_f32_16x16x32_f16 v[64:67], v[124:127], v[214:217], v[64:67]
	s_setprio 0
	s_setprio 1
	v_mfma_f32_16x16x32_f16 v[140:143], v[144:147], v[160:163], v[140:143]
	v_mfma_f32_16x16x32_f16 v[136:139], v[152:155], v[160:163], v[136:139]
	v_mfma_f32_16x16x32_f16 v[108:111], v[144:147], v[168:171], v[108:111]
	v_mfma_f32_16x16x32_f16 v[104:107], v[152:155], v[168:171], v[104:107]
	v_mfma_f32_16x16x32_f16 v[92:95], v[144:147], v[202:205], v[92:95]
	v_mfma_f32_16x16x32_f16 v[88:91], v[152:155], v[202:205], v[88:91]
	v_mfma_f32_16x16x32_f16 v[76:79], v[144:147], v[210:213], v[76:79]
	v_mfma_f32_16x16x32_f16 v[72:75], v[152:155], v[210:213], v[72:75]
	v_mfma_f32_16x16x32_f16 v[140:143], v[148:151], v[164:167], v[140:143]
	v_mfma_f32_16x16x32_f16 v[136:139], v[156:159], v[164:167], v[136:139]
	v_mfma_f32_16x16x32_f16 v[108:111], v[148:151], v[192:195], v[108:111]
	v_mfma_f32_16x16x32_f16 v[104:107], v[156:159], v[192:195], v[104:107]
	v_mfma_f32_16x16x32_f16 v[92:95], v[148:151], v[206:209], v[92:95]
	v_mfma_f32_16x16x32_f16 v[88:91], v[156:159], v[206:209], v[88:91]
	v_mfma_f32_16x16x32_f16 v[76:79], v[148:151], v[214:217], v[76:79]
	v_mfma_f32_16x16x32_f16 v[72:75], v[156:159], v[214:217], v[72:75]
	s_setprio 0
	s_barrier
	s_add_i32 s57, s51, s28
	v_lshl_add_u64 v[218:219], s[22:23], 0, v[174:175]
	s_mov_b32 m0, s57
	ds_read_b128 v[160:163], v200 offset:16384
	ds_read_b128 v[164:167], v200 offset:17408
	ds_read_b128 v[168:171], v200 offset:18432
	ds_read_b128 v[192:195], v200 offset:19456
	ds_read_b128 v[202:205], v200 offset:20480
	ds_read_b128 v[206:209], v200 offset:21504
	ds_read_b128 v[210:213], v200 offset:22528
	ds_read_b128 v[214:217], v200 offset:23552
	global_load_lds_dwordx4 v[218:219], off
	s_add_i32 m0, s57, 0x2000
	s_add_u32 s58, s22, 0x10000
	v_lshl_add_u64 v[220:221], s[22:23], 0, v[178:179]
	s_addc_u32 s59, s23, 0
	s_add_i32 s57, s52, s28
	global_load_lds_dwordx4 v[220:221], off
	v_lshl_add_u64 v[222:223], s[58:59], 0, v[174:175]
	s_mov_b32 m0, s57
	v_lshl_add_u64 v[224:225], s[26:27], 0, v[176:177]
	global_load_lds_dwordx4 v[222:223], off
	v_lshl_add_u64 v[222:223], s[58:59], 0, v[178:179]
	s_add_i32 m0, s57, 0x2000
	s_nop 0
	global_load_lds_dwordx4 v[222:223], off
	v_lshl_add_u64 v[222:223], s[26:27], 0, v[172:173]
	s_mov_b32 m0, s29
	s_nop 0
	global_load_lds_dwordx4 v[222:223], off
	s_mov_b32 m0, s41
	s_nop 0
	global_load_lds_dwordx4 v[224:225], off
	s_bitcmp1_b32 s101, 16
	s_cbranch_scc0 .Lpkb_w8b
	s_waitcnt vmcnt(9)
	s_branch .Lpkb_db

; #define PG8_STAGE(bufoff, gbase, voff) do { _Pragma("unroll") for (int _i = 0; _i < 2; ++_i) \
;         __builtin_amdgcn_global_load_lds((const unsigned*)((const char*)(gbase) + (voff)[_i]), (PG8_LAS unsigned*)(lds + (bufoff) + ldsw + _i * 8192), 16, 0, 0); } while (0)
; #define PG8_LDA(dst, b, h) do { _Pragma("unroll") for (int m = 0; m < 4; ++m) _Pragma("unroll") for (int k = 0; k < 2; ++k) dst[m][k] = *(const PG8_LAS bf16x8*)(lds + PG8_SA(b, h) + aoff + m * 2048 + k * 1024); } while (0)
; #define PG8_LDB(dst, b, h) do { _Pragma("unroll") for (int n = 0; n < 2; ++n) _Pragma("unroll") for (int k = 0; k < 2; ++k) dst[n][k] = *(const PG8_LAS bf16x8*)(lds + PG8_SB(b, h) + boff + n * 2048 + k * 1024); } while (0)
; #define PG8_WAIT_V(n) asm volatile("s_waitcnt vmcnt(" #n ")" ::: "memory")
; #define PG8_WAIT_L(n) asm volatile("s_waitcnt lgkmcnt(" #n ")" ::: "memory")
; #define PG8_BAR __builtin_amdgcn_s_barrier()
; #define PG8_SCHED __builtin_amdgcn_sched_barrier(0)
;     ...
;             PG8_WAIT_V(8); PG8_WAIT_L(0); PG8_BAR; PG8_MMA(1, 0, At, B0); PG8_MMA(1, 1, At, B1); PG8_BAR; PG8_SCHED;
;             PG8_LDB(B0, 1, 0); PG8_LDB(B1, 1, 1); PG8_SCHED; PG8_LDA(At, 1, 0); PG8_STAGE(PG8_SA(0, 1), a2 + hstep, voffA);
.Lpkb_db:
	s_waitcnt lgkmcnt(0)
	s_barrier
	s_setprio 1
	s_waitcnt lgkmcnt(0)
	v_mfma_f32_16x16x32_f16 v[52:55], v[112:115], v[160:163], v[52:55]
	v_mfma_f32_16x16x32_f16 v[48:51], v[120:123], v[160:163], v[48:51]
	v_mfma_f32_16x16x32_f16 v[36:39], v[112:115], v[168:171], v[36:39]
	v_mfma_f32_16x16x32_f16 v[32:35], v[120:123], v[168:171], v[32:35]
	v_mfma_f32_16x16x32_f16 v[20:23], v[112:115], v[202:205], v[20:23]
	v_mfma_f32_16x16x32_f16 v[16:19], v[120:123], v[202:205], v[16:19]
	v_mfma_f32_16x16x32_f16 v[4:7], v[112:115], v[210:213], v[4:7]
	v_mfma_f32_16x16x32_f16 v[0:3], v[120:123], v[210:213], v[0:3]
	v_mfma_f32_16x16x32_f16 v[52:55], v[116:119], v[164:167], v[52:55]
	v_mfma_f32_16x16x32_f16 v[48:51], v[124:127], v[164:167], v[48:51]
	v_mfma_f32_16x16x32_f16 v[36:39], v[116:119], v[192:195], v[36:39]
	v_mfma_f32_16x16x32_f16 v[32:35], v[124:127], v[192:195], v[32:35]
	v_mfma_f32_16x16x32_f16 v[20:23], v[116:119], v[206:209], v[20:23]
	v_mfma_f32_16x16x32_f16 v[16:19], v[124:127], v[206:209], v[16:19]
	v_mfma_f32_16x16x32_f16 v[4:7], v[116:119], v[214:217], v[4:7]
	v_mfma_f32_16x16x32_f16 v[0:3], v[124:127], v[214:217], v[0:3]
	s_setprio 0
	s_setprio 1
	v_mfma_f32_16x16x32_f16 v[60:63], v[144:147], v[160:163], v[60:63]
	v_mfma_f32_16x16x32_f16 v[56:59], v[152:155], v[160:163], v[56:59]
	v_mfma_f32_16x16x32_f16 v[44:47], v[144:147], v[168:171], v[44:47]
	v_mfma_f32_16x16x32_f16 v[40:43], v[152:155], v[168:171], v[40:43]
	v_mfma_f32_16x16x32_f16 v[28:31], v[144:147], v[202:205], v[28:31]
	v_mfma_f32_16x16x32_f16 v[24:27], v[152:155], v[202:205], v[24:27]
	v_mfma_f32_16x16x32_f16 v[12:15], v[144:147], v[210:213], v[12:15]
	v_mfma_f32_16x16x32_f16 v[8:11], v[152:155], v[210:213], v[8:11]
	v_mfma_f32_16x16x32_f16 v[60:63], v[148:151], v[164:167], v[60:63]
	v_mfma_f32_16x16x32_f16 v[56:59], v[156:159], v[164:167], v[56:59]
	v_mfma_f32_16x16x32_f16 v[44:47], v[148:151], v[192:195], v[44:47]
	v_mfma_f32_16x16x32_f16 v[40:43], v[156:159], v[192:195], v[40:43]
	v_mfma_f32_16x16x32_f16 v[28:31], v[148:151], v[206:209], v[28:31]
	v_mfma_f32_16x16x32_f16 v[24:27], v[156:159], v[206:209], v[24:27]
	v_mfma_f32_16x16x32_f16 v[12:15], v[148:151], v[214:217], v[12:15]
	v_mfma_f32_16x16x32_f16 v[8:11], v[156:159], v[214:217], v[8:11]
	s_setprio 0
	s_barrier
	s_add_i32 s57, 0, 0x18000
	s_add_i32 s58, 0, 0x1c000
	v_add_u32_e32 v124, s57, v197
	v_add_u32_e32 v156, s58, v197
	ds_read_b128 v[112:115], v124
	ds_read_b128 v[116:119], v124 offset:1024
	ds_read_b128 v[120:123], v124 offset:2048
	ds_read_b128 v[124:127], v124 offset:3072
	ds_read_b128 v[144:147], v156
	ds_read_b128 v[148:151], v156 offset:1024
	ds_read_b128 v[152:155], v156 offset:2048
	ds_read_b128 v[156:159], v156 offset:3072
	s_add_u32 s26, s26, 0x40000
	s_addc_u32 s27, s27, 0
	s_mov_b32 m0, s42
	v_lshl_add_u64 v[226:227], s[26:27], 0, v[172:173]
	ds_read_b128 v[160:163], v200 offset:32768
	ds_read_b128 v[164:167], v200 offset:33792
	ds_read_b128 v[168:171], v200 offset:34816
	ds_read_b128 v[192:195], v200 offset:35840
	ds_read_b128 v[202:205], v200 offset:36864
	ds_read_b128 v[206:209], v200 offset:37888
	ds_read_b128 v[210:213], v200 offset:38912
	ds_read_b128 v[214:217], v200 offset:39936
	global_load_lds_dwordx4 v[226:227], off
	v_lshl_add_u64 v[226:227], s[26:27], 0, v[176:177]
	s_mov_b32 m0, s43
	s_nop 0
	global_load_lds_dwordx4 v[226:227], off
	s_bitcmp1_b32 s101, 16
	s_cbranch_scc0 .Lpkb_w8c
	s_waitcnt vmcnt(9)
	s_branch .Lpkb_dc

; #define PG8_STAGE(bufoff, gbase, voff) do { _Pragma("unroll") for (int _i = 0; _i < 2; ++_i) \
;         __builtin_amdgcn_global_load_lds((const unsigned*)((const char*)(gbase) + (voff)[_i]), (PG8_LAS unsigned*)(lds + (bufoff) + ldsw + _i * 8192), 16, 0, 0); } while (0)
; #define PG8_LDA(dst, b, h) do { _Pragma("unroll") for (int m = 0; m < 4; ++m) _Pragma("unroll") for (int k = 0; k < 2; ++k) dst[m][k] = *(const PG8_LAS bf16x8*)(lds + PG8_SA(b, h) + aoff + m * 2048 + k * 1024); } while (0)
; #define PG8_WAIT_V(n) asm volatile("s_waitcnt vmcnt(" #n ")" ::: "memory")
; #define PG8_WAIT_L(n) asm volatile("s_waitcnt lgkmcnt(" #n ")" ::: "memory")
; #define PG8_BAR __builtin_amdgcn_s_barrier()
; #define PG8_SCHED __builtin_amdgcn_sched_barrier(0)
;     ...
;             PG8_WAIT_V(8); PG8_WAIT_L(0); PG8_BAR; PG8_MMA(0, 0, At, B0); PG8_MMA(0, 1, At, B1); PG8_BAR; PG8_SCHED;
;             PG8_LDA(At, 1, 1); PG8_STAGE(PG8_SB(1, 0), b3, voffB); PG8_STAGE(PG8_SB(1, 1), b3 + hstepB, voffB); PG8_STAGE(PG8_SA(1, 0), a3, voffA);
;             PG8_WAIT_V(8); PG8_WAIT_L(0); PG8_BAR; PG8_MMA(1, 0, At, B0); PG8_MMA(1, 1, At, B1); PG8_BAR; PG8_SCHED;
;         }
.Lpkb_dc:
	s_waitcnt lgkmcnt(0)
	s_barrier
	s_setprio 1
	s_waitcnt lgkmcnt(0)
	v_mfma_f32_16x16x32_f16 v[132:135], v[112:115], v[160:163], v[132:135]
	v_mfma_f32_16x16x32_f16 v[128:131], v[120:123], v[160:163], v[128:131]
	v_mfma_f32_16x16x32_f16 v[100:103], v[112:115], v[168:171], v[100:103]
	v_mfma_f32_16x16x32_f16 v[96:99], v[120:123], v[168:171], v[96:99]
	v_mfma_f32_16x16x32_f16 v[84:87], v[112:115], v[202:205], v[84:87]
	v_mfma_f32_16x16x32_f16 v[80:83], v[120:123], v[202:205], v[80:83]
	v_mfma_f32_16x16x32_f16 v[68:71], v[112:115], v[210:213], v[68:71]
	v_mfma_f32_16x16x32_f16 v[64:67], v[120:123], v[210:213], v[64:67]
	v_mfma_f32_16x16x32_f16 v[132:135], v[116:119], v[164:167], v[132:135]
	v_mfma_f32_16x16x32_f16 v[128:131], v[124:127], v[164:167], v[128:131]
	v_mfma_f32_16x16x32_f16 v[100:103], v[116:119], v[192:195], v[100:103]
	v_mfma_f32_16x16x32_f16 v[96:99], v[124:127], v[192:195], v[96:99]
	v_mfma_f32_16x16x32_f16 v[84:87], v[116:119], v[206:209], v[84:87]
	v_mfma_f32_16x16x32_f16 v[80:83], v[124:127], v[206:209], v[80:83]
	v_mfma_f32_16x16x32_f16 v[68:71], v[116:119], v[214:217], v[68:71]
	v_mfma_f32_16x16x32_f16 v[64:67], v[124:127], v[214:217], v[64:67]
	s_setprio 0
	s_setprio 1
	v_mfma_f32_16x16x32_f16 v[140:143], v[144:147], v[160:163], v[140:143]
	v_mfma_f32_16x16x32_f16 v[136:139], v[152:155], v[160:163], v[136:139]
	v_mfma_f32_16x16x32_f16 v[108:111], v[144:147], v[168:171], v[108:111]
	v_mfma_f32_16x16x32_f16 v[104:107], v[152:155], v[168:171], v[104:107]
	v_mfma_f32_16x16x32_f16 v[92:95], v[144:147], v[202:205], v[92:95]
	v_mfma_f32_16x16x32_f16 v[88:91], v[152:155], v[202:205], v[88:91]
	v_mfma_f32_16x16x32_f16 v[76:79], v[144:147], v[210:213], v[76:79]
	v_mfma_f32_16x16x32_f16 v[72:75], v[152:155], v[210:213], v[72:75]
	v_mfma_f32_16x16x32_f16 v[140:143], v[148:151], v[164:167], v[140:143]
	v_mfma_f32_16x16x32_f16 v[136:139], v[156:159], v[164:167], v[136:139]
	v_mfma_f32_16x16x32_f16 v[108:111], v[148:151], v[192:195], v[108:111]
	v_mfma_f32_16x16x32_f16 v[104:107], v[156:159], v[192:195], v[104:107]
	v_mfma_f32_16x16x32_f16 v[92:95], v[148:151], v[206:209], v[92:95]
	v_mfma_f32_16x16x32_f16 v[88:91], v[156:159], v[206:209], v[88:91]
	v_mfma_f32_16x16x32_f16 v[76:79], v[148:151], v[214:217], v[76:79]
	v_mfma_f32_16x16x32_f16 v[72:75], v[156:159], v[214:217], v[72:75]
	s_setprio 0
	s_barrier
	s_add_i32 s26, s57, s28
	v_lshl_add_u64 v[218:219], v[218:219], 0, s[10:11]
	s_mov_b32 m0, s26
	ds_read_b128 v[160:163], v200 offset:49152
	ds_read_b128 v[164:167], v200 offset:50176
	ds_read_b128 v[168:171], v200 offset:51200
	ds_read_b128 v[192:195], v200 offset:52224
	ds_read_b128 v[202:205], v200 offset:53248
	ds_read_b128 v[206:209], v200 offset:54272
	ds_read_b128 v[210:213], v200 offset:55296
	ds_read_b128 v[214:217], v200 offset:56320
	global_load_lds_dwordx4 v[218:219], off
	s_add_i32 m0, s26, 0x2000
	s_add_u32 s22, s22, 0x10080
	v_lshl_add_u64 v[218:219], v[220:221], 0, s[10:11]
	s_addc_u32 s23, s23, 0
	s_add_i32 s26, s58, s28
	global_load_lds_dwordx4 v[218:219], off
	v_lshl_add_u64 v[218:219], s[22:23], 0, v[174:175]
	s_mov_b32 m0, s26
	s_nop 0
	global_load_lds_dwordx4 v[218:219], off
	v_lshl_add_u64 v[218:219], s[22:23], 0, v[178:179]
	s_add_i32 m0, s26, 0x2000
	s_nop 0
	global_load_lds_dwordx4 v[218:219], off
	v_lshl_add_u64 v[218:219], v[222:223], 0, s[10:11]
	s_mov_b32 m0, s48
	s_nop 0
	global_load_lds_dwordx4 v[218:219], off
	v_lshl_add_u64 v[218:219], v[224:225], 0, s[10:11]
	s_mov_b32 m0, s49
	s_nop 0
	global_load_lds_dwordx4 v[218:219], off
	s_waitcnt vmcnt(8)
	s_waitcnt lgkmcnt(0)
	s_barrier
	s_setprio 1
	s_waitcnt lgkmcnt(0)
	v_mfma_f32_16x16x32_f16 v[52:55], v[112:115], v[160:163], v[52:55]
	v_mfma_f32_16x16x32_f16 v[48:51], v[120:123], v[160:163], v[48:51]
	v_mfma_f32_16x16x32_f16 v[36:39], v[112:115], v[168:171], v[36:39]
	v_mfma_f32_16x16x32_f16 v[32:35], v[120:123], v[168:171], v[32:35]
	v_mfma_f32_16x16x32_f16 v[20:23], v[112:115], v[202:205], v[20:23]
	v_mfma_f32_16x16x32_f16 v[16:19], v[120:123], v[202:205], v[16:19]
	v_mfma_f32_16x16x32_f16 v[4:7], v[112:115], v[210:213], v[4:7]
	v_mfma_f32_16x16x32_f16 v[0:3], v[120:123], v[210:213], v[0:3]
	v_mfma_f32_16x16x32_f16 v[52:55], v[116:119], v[164:167], v[52:55]
	v_mfma_f32_16x16x32_f16 v[48:51], v[124:127], v[164:167], v[48:51]
	v_mfma_f32_16x16x32_f16 v[36:39], v[116:119], v[192:195], v[36:39]
	v_mfma_f32_16x16x32_f16 v[32:35], v[124:127], v[192:195], v[32:35]
	v_mfma_f32_16x16x32_f16 v[20:23], v[116:119], v[206:209], v[20:23]
	v_mfma_f32_16x16x32_f16 v[16:19], v[124:127], v[206:209], v[16:19]
	v_mfma_f32_16x16x32_f16 v[4:7], v[116:119], v[214:217], v[4:7]
	v_mfma_f32_16x16x32_f16 v[0:3], v[124:127], v[214:217], v[0:3]
	s_setprio 0
	s_setprio 1
	v_mfma_f32_16x16x32_f16 v[60:63], v[144:147], v[160:163], v[60:63]
	v_mfma_f32_16x16x32_f16 v[56:59], v[152:155], v[160:163], v[56:59]
	v_mfma_f32_16x16x32_f16 v[44:47], v[144:147], v[168:171], v[44:47]
	v_mfma_f32_16x16x32_f16 v[40:43], v[152:155], v[168:171], v[40:43]
	v_mfma_f32_16x16x32_f16 v[28:31], v[144:147], v[202:205], v[28:31]
	v_mfma_f32_16x16x32_f16 v[24:27], v[152:155], v[202:205], v[24:27]
	v_mfma_f32_16x16x32_f16 v[12:15], v[144:147], v[210:213], v[12:15]
	v_mfma_f32_16x16x32_f16 v[8:11], v[152:155], v[210:213], v[8:11]
	v_mfma_f32_16x16x32_f16 v[60:63], v[148:151], v[164:167], v[60:63]
	v_mfma_f32_16x16x32_f16 v[56:59], v[156:159], v[164:167], v[56:59]
	v_mfma_f32_16x16x32_f16 v[44:47], v[148:151], v[192:195], v[44:47]
	v_mfma_f32_16x16x32_f16 v[40:43], v[156:159], v[192:195], v[40:43]
	v_mfma_f32_16x16x32_f16 v[28:31], v[148:151], v[206:209], v[28:31]
	v_mfma_f32_16x16x32_f16 v[24:27], v[156:159], v[206:209], v[24:27]
	v_mfma_f32_16x16x32_f16 v[12:15], v[148:151], v[214:217], v[12:15]
	v_mfma_f32_16x16x32_f16 v[8:11], v[156:159], v[214:217], v[8:11]
	s_setprio 0
	s_barrier
	s_bitcmp1_b32 s101, 16
	s_cbranch_scc0 .Lpkb_t
	s_and_b32 s101, s101, 0xff
	s_sub_u32 s101, s101, 1
